# v97 + the same static-priority treatment for the q/kv up-projection and memory K/V GEMM loops (timing 1)
# speedup vs baseline: 1.0167x; 1.0003x over previous
.LBB0_93:
	s_add_u32 s14, s74, 0x37400000
	s_addc_u32 s15, s75, 0
	s_add_u32 s44, s74, 0xac00000
	s_addc_u32 s45, s75, 0
	s_lshl_b32 s8, s8, 5
	s_and_b32 s8, s8, 0x60
	s_add_i32 m0, s34, 0x18000
	v_lshl_add_u64 v[6:7], v[6:7], 0, s[26:27]
	s_lshl_b32 s38, s12, 6
	s_lshl_b32 s20, s12, 13
	s_lshl_b32 s21, s8, 7
	s_waitcnt vmcnt(4)
	s_barrier
	global_load_lds_dwordx4 v[6:7], off
	v_lshl_add_u64 v[4:5], v[4:5], 0, s[26:27]
	s_add_i32 m0, s34, 0x1a000
	s_add_i32 s39, s34, 0x8000
	s_add_i32 s46, s34, 0xa000
	global_load_lds_dwordx4 v[4:5], off
	v_lshl_add_u64 v[0:1], v[0:1], 0, s[26:27]
	s_mov_b32 m0, s39
	s_add_u32 s12, s60, 0x20080
	global_load_lds_dwordx4 v[0:1], off
	v_lshl_add_u64 v[0:1], v[2:3], 0, s[26:27]
	s_mov_b32 m0, s46
	s_addc_u32 s13, s61, 0
	global_load_lds_dwordx4 v[0:1], off
	s_add_i32 m0, s34, 0x1c000
	v_lshl_add_u64 v[0:1], s[12:13], 0, v[184:185]
	global_load_lds_dwordx4 v[0:1], off
	v_lshl_add_u64 v[0:1], s[12:13], 0, v[192:193]
	s_add_i32 m0, s34, 0x1e000
	v_and_b32_e32 v214, 15, v8
	global_load_lds_dwordx4 v[0:1], off
	v_lshrrev_b32_e32 v0, 1, v8
	v_and_b32_e32 v0, 24, v0
	v_lshlrev_b32_e32 v1, 1, v0
	v_lshlrev_b32_e32 v2, 2, v8
	v_lshl_or_b32 v1, v214, 6, v1
	v_and_b32_e32 v2, 32, v2
	s_movk_i32 s13, 0x1400
	v_bitop3_b32 v3, v1, s20, v2 bitop3:0xde
	v_bitop3_b32 v215, v1, s21, v2 bitop3:0xde
	v_or_b32_e32 v216, s8, v0
	v_lshrrev_b32_e32 v1, 1, v14
	v_mul_lo_u32 v0, v13, s13
	s_mov_b32 s12, 0x14000
	s_cmpk_lt_u32 s9, 0x100
	v_mad_u64_u32 v[0:1], s[8:9], v1, s12, v[0:1]
	v_or_b32_e32 v0, v0, v15
	v_add_lshl_u32 v0, v0, v16, 1
	v_mov_b32_e32 v1, v185
	s_mov_b64 s[20:21], 0x140080
	v_lshl_add_u64 v[198:199], v[0:1], 0, s[20:21]
	v_lshrrev_b32_e32 v1, 1, v9
	v_mul_lo_u32 v0, v10, s13
	v_mad_u64_u32 v[0:1], s[8:9], v1, s12, v[0:1]
	s_waitcnt vmcnt(6)
	v_or_b32_e32 v0, v0, v11
	v_add_lshl_u32 v0, v0, v12, 1
	v_mov_b32_e32 v1, v185
	s_cselect_b64 s[48:49], -1, 0
	s_mov_b32 s70, 0x14000
	v_lshl_add_u64 v[200:201], v[0:1], 0, s[20:21]
	s_mov_b32 s9, 0
	v_add_u32_e32 v217, 0, v3
	v_readlane_b32 s50, v255, 18
	v_readlane_b32 s51, v255, 17
	s_barrier
	v_readfirstlane_b32 s98, v203
	s_nop 3
	s_lshr_b32 s98, s98, 8
	s_cmp_lg_u32 s98, 0
	s_cbranch_scc0 .Lgp_96
	s_setprio 1

.LBB0_101:
	s_add_u32 s42, s58, 0x100
	s_addc_u32 s43, s59, 0
	s_add_i32 s8, 0, 0x10000
	v_add_u32_e32 v140, s8, v215
	ds_read_b128 v[128:131], v140
	ds_read_b128 v[132:135], v140 offset:1024
	ds_read_b128 v[136:139], v140 offset:2048
	ds_read_b128 v[140:143], v140 offset:3072
	s_cmp_eq_u32 s65, 4
	s_cselect_b32 s13, s55, s43
	s_cselect_b32 s12, s54, s42
	s_cselect_b32 s61, s53, s64
	s_cselect_b32 s60, s62, s63
	v_lshl_add_u64 v[176:177], s[58:59], 0, v[198:199]
	s_add_i32 m0, s34, 0xc000
	ds_read_b128 v[144:147], v217
	ds_read_b128 v[148:151], v217 offset:1024
	ds_read_b128 v[152:155], v217 offset:2048
	ds_read_b128 v[156:159], v217 offset:3072
	ds_read_b128 v[160:163], v217 offset:4096
	ds_read_b128 v[164:167], v217 offset:5120
	ds_read_b128 v[168:171], v217 offset:6144
	ds_read_b128 v[172:175], v217 offset:7168
	global_load_lds_dwordx4 v[176:177], off
	v_lshl_add_u64 v[176:177], s[58:59], 0, v[200:201]
	s_add_i32 m0, s34, 0xe000
	s_nop 0
	global_load_lds_dwordx4 v[176:177], off
	s_waitcnt lgkmcnt(8)
	s_barrier
	s_waitcnt lgkmcnt(0)
	s_waitcnt lgkmcnt(0)
	v_mfma_f32_16x16x32_bf16 v[124:127], v[128:131], v[144:147], v[124:127]
	v_mfma_f32_16x16x32_bf16 v[120:123], v[136:139], v[144:147], v[120:123]
	v_mfma_f32_16x16x32_bf16 v[112:115], v[128:131], v[152:155], v[112:115]
	v_mfma_f32_16x16x32_bf16 v[104:107], v[136:139], v[152:155], v[104:107]
	v_mfma_f32_16x16x32_bf16 v[96:99], v[128:131], v[160:163], v[96:99]
	v_mfma_f32_16x16x32_bf16 v[88:91], v[136:139], v[160:163], v[88:91]
	v_mfma_f32_16x16x32_bf16 v[80:83], v[128:131], v[168:171], v[80:83]
	v_mfma_f32_16x16x32_bf16 v[72:75], v[136:139], v[168:171], v[72:75]
	v_mfma_f32_16x16x32_bf16 v[124:127], v[132:135], v[148:151], v[124:127]
	v_mfma_f32_16x16x32_bf16 v[120:123], v[140:143], v[148:151], v[120:123]
	v_mfma_f32_16x16x32_bf16 v[112:115], v[132:135], v[156:159], v[112:115]
	v_mfma_f32_16x16x32_bf16 v[104:107], v[140:143], v[156:159], v[104:107]
	v_mfma_f32_16x16x32_bf16 v[96:99], v[132:135], v[164:167], v[96:99]
	v_mfma_f32_16x16x32_bf16 v[88:91], v[140:143], v[164:167], v[88:91]
	v_mfma_f32_16x16x32_bf16 v[80:83], v[132:135], v[172:175], v[80:83]
	v_mfma_f32_16x16x32_bf16 v[72:75], v[140:143], v[172:175], v[72:75]
	s_barrier
	s_add_i32 s33, 0, 0x14000
	v_add_u32_e32 v186, s33, v215
	s_add_i32 s8, s8, s31
	ds_read_b128 v[176:179], v186
	ds_read_b128 v[180:183], v186 offset:1024
	ds_read_b128 v[218:221], v186 offset:2048
	ds_read_b128 v[222:225], v186 offset:3072
	v_lshl_add_u64 v[186:187], s[60:61], 0, v[184:185]
	s_mov_b32 m0, s8
	v_lshl_add_u64 v[188:189], s[60:61], 0, v[192:193]
	global_load_lds_dwordx4 v[186:187], off
	s_add_i32 m0, s8, 0x2000
	s_nop 0
	global_load_lds_dwordx4 v[188:189], off
	s_barrier
	s_waitcnt lgkmcnt(0)
	s_waitcnt lgkmcnt(0)
	v_mfma_f32_16x16x32_bf16 v[116:119], v[176:179], v[144:147], v[116:119]
	v_mfma_f32_16x16x32_bf16 v[108:111], v[218:221], v[144:147], v[108:111]
	v_mfma_f32_16x16x32_bf16 v[100:103], v[176:179], v[152:155], v[100:103]
	v_mfma_f32_16x16x32_bf16 v[92:95], v[218:221], v[152:155], v[92:95]
	v_mfma_f32_16x16x32_bf16 v[84:87], v[176:179], v[160:163], v[84:87]
	v_mfma_f32_16x16x32_bf16 v[76:79], v[218:221], v[160:163], v[76:79]
	v_mfma_f32_16x16x32_bf16 v[68:71], v[176:179], v[168:171], v[68:71]
	v_mfma_f32_16x16x32_bf16 v[64:67], v[218:221], v[168:171], v[64:67]
	v_mfma_f32_16x16x32_bf16 v[116:119], v[180:183], v[148:151], v[116:119]
	v_mfma_f32_16x16x32_bf16 v[108:111], v[222:225], v[148:151], v[108:111]
	v_mfma_f32_16x16x32_bf16 v[100:103], v[180:183], v[156:159], v[100:103]
	v_mfma_f32_16x16x32_bf16 v[92:95], v[222:225], v[156:159], v[92:95]
	v_mfma_f32_16x16x32_bf16 v[84:87], v[180:183], v[164:167], v[84:87]
	v_mfma_f32_16x16x32_bf16 v[76:79], v[222:225], v[164:167], v[76:79]
	v_mfma_f32_16x16x32_bf16 v[68:71], v[180:183], v[172:175], v[68:71]
	v_mfma_f32_16x16x32_bf16 v[64:67], v[222:225], v[172:175], v[64:67]
	s_mov_b32 m0, s34
	v_lshl_add_u64 v[226:227], s[12:13], 0, v[196:197]
	s_barrier
	ds_read_b128 v[144:147], v217 offset:16384
	ds_read_b128 v[148:151], v217 offset:17408
	ds_read_b128 v[152:155], v217 offset:18432
	ds_read_b128 v[156:159], v217 offset:19456
	ds_read_b128 v[160:163], v217 offset:20480
	ds_read_b128 v[164:167], v217 offset:21504
	ds_read_b128 v[168:171], v217 offset:22528
	ds_read_b128 v[172:175], v217 offset:23552
	global_load_lds_dwordx4 v[226:227], off
	v_lshl_add_u64 v[228:229], s[12:13], 0, v[194:195]
	s_mov_b32 m0, s35
	s_nop 0
	global_load_lds_dwordx4 v[228:229], off
	s_barrier
	s_waitcnt lgkmcnt(0)
	s_waitcnt lgkmcnt(0)
	v_mfma_f32_16x16x32_bf16 v[60:63], v[128:131], v[144:147], v[60:63]
	v_mfma_f32_16x16x32_bf16 v[56:59], v[136:139], v[144:147], v[56:59]
	v_mfma_f32_16x16x32_bf16 v[48:51], v[128:131], v[152:155], v[48:51]
	v_mfma_f32_16x16x32_bf16 v[40:43], v[136:139], v[152:155], v[40:43]
	v_mfma_f32_16x16x32_bf16 v[32:35], v[128:131], v[160:163], v[32:35]
	v_mfma_f32_16x16x32_bf16 v[24:27], v[136:139], v[160:163], v[24:27]
	v_mfma_f32_16x16x32_bf16 v[16:19], v[128:131], v[168:171], v[16:19]
	v_mfma_f32_16x16x32_bf16 v[8:11], v[136:139], v[168:171], v[8:11]
	v_mfma_f32_16x16x32_bf16 v[60:63], v[132:135], v[148:151], v[60:63]
	v_mfma_f32_16x16x32_bf16 v[56:59], v[140:143], v[148:151], v[56:59]
	v_mfma_f32_16x16x32_bf16 v[48:51], v[132:135], v[156:159], v[48:51]
	v_mfma_f32_16x16x32_bf16 v[40:43], v[140:143], v[156:159], v[40:43]
	v_mfma_f32_16x16x32_bf16 v[32:35], v[132:135], v[164:167], v[32:35]
	v_mfma_f32_16x16x32_bf16 v[24:27], v[140:143], v[164:167], v[24:27]
	v_mfma_f32_16x16x32_bf16 v[16:19], v[132:135], v[172:175], v[16:19]
	v_mfma_f32_16x16x32_bf16 v[8:11], v[140:143], v[172:175], v[8:11]
	s_barrier
	s_add_u32 s20, s60, 0x20000
	s_addc_u32 s21, s61, 0
	s_add_i32 s8, s33, s31
	v_lshl_add_u64 v[128:129], s[20:21], 0, v[184:185]
	s_mov_b32 m0, s8
	s_nop 0
	global_load_lds_dwordx4 v[128:129], off
	v_lshl_add_u64 v[128:129], s[20:21], 0, v[192:193]
	s_add_i32 m0, s8, 0x2000
	s_nop 0
	global_load_lds_dwordx4 v[128:129], off
	s_waitcnt vmcnt(6)
	s_barrier
	v_mfma_f32_16x16x32_bf16 v[52:55], v[176:179], v[144:147], v[52:55]
	v_mfma_f32_16x16x32_bf16 v[44:47], v[218:221], v[144:147], v[44:47]
	v_mfma_f32_16x16x32_bf16 v[36:39], v[176:179], v[152:155], v[36:39]
	v_mfma_f32_16x16x32_bf16 v[28:31], v[218:221], v[152:155], v[28:31]
	v_mfma_f32_16x16x32_bf16 v[20:23], v[176:179], v[160:163], v[20:23]
	v_mfma_f32_16x16x32_bf16 v[12:15], v[218:221], v[160:163], v[12:15]
	v_mfma_f32_16x16x32_bf16 v[4:7], v[176:179], v[168:171], v[4:7]
	v_mfma_f32_16x16x32_bf16 v[0:3], v[218:221], v[168:171], v[0:3]
	v_mfma_f32_16x16x32_bf16 v[52:55], v[180:183], v[148:151], v[52:55]
	v_mfma_f32_16x16x32_bf16 v[44:47], v[222:225], v[148:151], v[44:47]
	v_mfma_f32_16x16x32_bf16 v[36:39], v[180:183], v[156:159], v[36:39]
	v_mfma_f32_16x16x32_bf16 v[28:31], v[222:225], v[156:159], v[28:31]
	v_mfma_f32_16x16x32_bf16 v[20:23], v[180:183], v[164:167], v[20:23]
	v_mfma_f32_16x16x32_bf16 v[12:15], v[222:225], v[164:167], v[12:15]
	v_mfma_f32_16x16x32_bf16 v[4:7], v[180:183], v[172:175], v[4:7]
	v_mfma_f32_16x16x32_bf16 v[0:3], v[222:225], v[172:175], v[0:3]
	s_add_i32 s8, 0, 0x18000
	v_add_u32_e32 v140, s8, v215
	s_barrier
	ds_read_b128 v[128:131], v140
	ds_read_b128 v[132:135], v140 offset:1024
	ds_read_b128 v[136:139], v140 offset:2048
	ds_read_b128 v[140:143], v140 offset:3072
	s_add_u32 s12, s12, 0x140000
	s_addc_u32 s13, s13, 0
	s_mov_b32 m0, s36
	v_lshl_add_u64 v[176:177], s[12:13], 0, v[196:197]
	ds_read_b128 v[144:147], v217 offset:32768
	ds_read_b128 v[148:151], v217 offset:33792
	ds_read_b128 v[152:155], v217 offset:34816
	ds_read_b128 v[156:159], v217 offset:35840
	ds_read_b128 v[160:163], v217 offset:36864
	ds_read_b128 v[164:167], v217 offset:37888
	ds_read_b128 v[168:171], v217 offset:38912
	ds_read_b128 v[172:175], v217 offset:39936
	global_load_lds_dwordx4 v[176:177], off
	v_lshl_add_u64 v[176:177], s[12:13], 0, v[194:195]
	s_mov_b32 m0, s37
	s_nop 0
	global_load_lds_dwordx4 v[176:177], off
	s_waitcnt lgkmcnt(8)
	s_barrier
	s_waitcnt lgkmcnt(0)
	s_waitcnt lgkmcnt(0)
	v_mfma_f32_16x16x32_bf16 v[124:127], v[128:131], v[144:147], v[124:127]
	v_mfma_f32_16x16x32_bf16 v[120:123], v[136:139], v[144:147], v[120:123]
	v_mfma_f32_16x16x32_bf16 v[112:115], v[128:131], v[152:155], v[112:115]
	v_mfma_f32_16x16x32_bf16 v[104:107], v[136:139], v[152:155], v[104:107]
	v_mfma_f32_16x16x32_bf16 v[96:99], v[128:131], v[160:163], v[96:99]
	v_mfma_f32_16x16x32_bf16 v[88:91], v[136:139], v[160:163], v[88:91]
	v_mfma_f32_16x16x32_bf16 v[80:83], v[128:131], v[168:171], v[80:83]
	v_mfma_f32_16x16x32_bf16 v[72:75], v[136:139], v[168:171], v[72:75]
	v_mfma_f32_16x16x32_bf16 v[124:127], v[132:135], v[148:151], v[124:127]
	v_mfma_f32_16x16x32_bf16 v[120:123], v[140:143], v[148:151], v[120:123]
	v_mfma_f32_16x16x32_bf16 v[112:115], v[132:135], v[156:159], v[112:115]
	v_mfma_f32_16x16x32_bf16 v[104:107], v[140:143], v[156:159], v[104:107]
	v_mfma_f32_16x16x32_bf16 v[96:99], v[132:135], v[164:167], v[96:99]
	v_mfma_f32_16x16x32_bf16 v[88:91], v[140:143], v[164:167], v[88:91]
	v_mfma_f32_16x16x32_bf16 v[80:83], v[132:135], v[172:175], v[80:83]
	v_mfma_f32_16x16x32_bf16 v[72:75], v[140:143], v[172:175], v[72:75]
	s_barrier
	s_add_i32 s20, 0, 0x1c000
	s_add_i32 s8, s8, s31
	v_add_u32_e32 v202, s20, v215
	v_lshl_add_u64 v[186:187], v[186:187], 0, s[26:27]
	s_mov_b32 m0, s8
	ds_read_b128 v[176:179], v202
	ds_read_b128 v[180:183], v202 offset:1024
	ds_read_b128 v[218:221], v202 offset:2048
	ds_read_b128 v[222:225], v202 offset:3072
	global_load_lds_dwordx4 v[186:187], off
	v_lshl_add_u64 v[186:187], v[188:189], 0, s[26:27]
	s_add_i32 m0, s8, 0x2000
	s_nop 0
	global_load_lds_dwordx4 v[186:187], off
	s_barrier
	s_waitcnt lgkmcnt(0)
	s_waitcnt lgkmcnt(0)
	v_mfma_f32_16x16x32_bf16 v[116:119], v[176:179], v[144:147], v[116:119]
	v_mfma_f32_16x16x32_bf16 v[108:111], v[218:221], v[144:147], v[108:111]
	v_mfma_f32_16x16x32_bf16 v[100:103], v[176:179], v[152:155], v[100:103]
	v_mfma_f32_16x16x32_bf16 v[92:95], v[218:221], v[152:155], v[92:95]
	v_mfma_f32_16x16x32_bf16 v[84:87], v[176:179], v[160:163], v[84:87]
	v_mfma_f32_16x16x32_bf16 v[76:79], v[218:221], v[160:163], v[76:79]
	v_mfma_f32_16x16x32_bf16 v[68:71], v[176:179], v[168:171], v[68:71]
	v_mfma_f32_16x16x32_bf16 v[64:67], v[218:221], v[168:171], v[64:67]
	v_mfma_f32_16x16x32_bf16 v[116:119], v[180:183], v[148:151], v[116:119]
	v_mfma_f32_16x16x32_bf16 v[108:111], v[222:225], v[148:151], v[108:111]
	v_mfma_f32_16x16x32_bf16 v[100:103], v[180:183], v[156:159], v[100:103]
	v_mfma_f32_16x16x32_bf16 v[92:95], v[222:225], v[156:159], v[92:95]
	v_mfma_f32_16x16x32_bf16 v[84:87], v[180:183], v[164:167], v[84:87]
	v_mfma_f32_16x16x32_bf16 v[76:79], v[222:225], v[164:167], v[76:79]
	v_mfma_f32_16x16x32_bf16 v[68:71], v[180:183], v[172:175], v[68:71]
	v_mfma_f32_16x16x32_bf16 v[64:67], v[222:225], v[172:175], v[64:67]
	s_mov_b32 m0, s39
	v_lshl_add_u64 v[186:187], v[226:227], 0, s[26:27]
	s_barrier
	ds_read_b128 v[144:147], v217 offset:49152
	ds_read_b128 v[148:151], v217 offset:50176
	ds_read_b128 v[152:155], v217 offset:51200
	ds_read_b128 v[156:159], v217 offset:52224
	ds_read_b128 v[160:163], v217 offset:53248
	ds_read_b128 v[164:167], v217 offset:54272
	ds_read_b128 v[168:171], v217 offset:55296
	ds_read_b128 v[172:175], v217 offset:56320
	global_load_lds_dwordx4 v[186:187], off
	v_lshl_add_u64 v[186:187], v[228:229], 0, s[26:27]
	s_mov_b32 m0, s46
	s_nop 0
	global_load_lds_dwordx4 v[186:187], off
	s_barrier
	s_waitcnt lgkmcnt(0)
	s_waitcnt lgkmcnt(0)
	v_mfma_f32_16x16x32_bf16 v[60:63], v[128:131], v[144:147], v[60:63]
	v_mfma_f32_16x16x32_bf16 v[56:59], v[136:139], v[144:147], v[56:59]
	v_mfma_f32_16x16x32_bf16 v[48:51], v[128:131], v[152:155], v[48:51]
	v_mfma_f32_16x16x32_bf16 v[40:43], v[136:139], v[152:155], v[40:43]
	v_mfma_f32_16x16x32_bf16 v[32:35], v[128:131], v[160:163], v[32:35]
	v_mfma_f32_16x16x32_bf16 v[24:27], v[136:139], v[160:163], v[24:27]
	v_mfma_f32_16x16x32_bf16 v[16:19], v[128:131], v[168:171], v[16:19]
	v_mfma_f32_16x16x32_bf16 v[8:11], v[136:139], v[168:171], v[8:11]
	v_mfma_f32_16x16x32_bf16 v[60:63], v[132:135], v[148:151], v[60:63]
	v_mfma_f32_16x16x32_bf16 v[56:59], v[140:143], v[148:151], v[56:59]
	v_mfma_f32_16x16x32_bf16 v[48:51], v[132:135], v[156:159], v[48:51]
	v_mfma_f32_16x16x32_bf16 v[40:43], v[140:143], v[156:159], v[40:43]
	v_mfma_f32_16x16x32_bf16 v[32:35], v[132:135], v[164:167], v[32:35]
	v_mfma_f32_16x16x32_bf16 v[24:27], v[140:143], v[164:167], v[24:27]
	v_mfma_f32_16x16x32_bf16 v[16:19], v[132:135], v[172:175], v[16:19]
	v_mfma_f32_16x16x32_bf16 v[8:11], v[140:143], v[172:175], v[8:11]
	s_barrier
	s_add_u32 s12, s60, 0x20080
	s_addc_u32 s13, s61, 0
	s_add_i32 s8, s20, s31
	v_lshl_add_u64 v[128:129], s[12:13], 0, v[184:185]
	s_mov_b32 m0, s8
	s_nop 0
	global_load_lds_dwordx4 v[128:129], off
	v_lshl_add_u64 v[128:129], s[12:13], 0, v[192:193]
	s_add_i32 m0, s8, 0x2000
	s_nop 0
	global_load_lds_dwordx4 v[128:129], off
	s_waitcnt vmcnt(6)
	s_barrier
	v_mfma_f32_16x16x32_bf16 v[52:55], v[176:179], v[144:147], v[52:55]
	v_mfma_f32_16x16x32_bf16 v[44:47], v[218:221], v[144:147], v[44:47]
	v_mfma_f32_16x16x32_bf16 v[36:39], v[176:179], v[152:155], v[36:39]
	v_mfma_f32_16x16x32_bf16 v[28:31], v[218:221], v[152:155], v[28:31]
	v_mfma_f32_16x16x32_bf16 v[20:23], v[176:179], v[160:163], v[20:23]
	v_mfma_f32_16x16x32_bf16 v[12:15], v[218:221], v[160:163], v[12:15]
	v_mfma_f32_16x16x32_bf16 v[4:7], v[176:179], v[168:171], v[4:7]
	v_mfma_f32_16x16x32_bf16 v[0:3], v[218:221], v[168:171], v[0:3]
	v_mfma_f32_16x16x32_bf16 v[52:55], v[180:183], v[148:151], v[52:55]
	v_mfma_f32_16x16x32_bf16 v[44:47], v[222:225], v[148:151], v[44:47]
	v_mfma_f32_16x16x32_bf16 v[36:39], v[180:183], v[156:159], v[36:39]
	v_mfma_f32_16x16x32_bf16 v[28:31], v[222:225], v[156:159], v[28:31]
	v_mfma_f32_16x16x32_bf16 v[20:23], v[180:183], v[164:167], v[20:23]
	v_mfma_f32_16x16x32_bf16 v[12:15], v[222:225], v[164:167], v[12:15]
	v_mfma_f32_16x16x32_bf16 v[4:7], v[180:183], v[172:175], v[4:7]
	v_mfma_f32_16x16x32_bf16 v[0:3], v[222:225], v[172:175], v[0:3]
	s_add_i32 s65, s65, 2
	s_add_u32 s63, s63, 0x100
	s_addc_u32 s64, s64, 0
	s_cmp_gt_u32 s65, 5
	s_mov_b64 s[58:59], s[42:43]
	s_barrier
	s_cbranch_scc0 .LBB0_101
	s_movk_i32 s64, 0xe7f0
	s_and_b64 vcc, exec, s[48:49]
	s_mov_b32 s65, -1
	s_cbranch_vccz .LBB0_104
	s_barrier

.LBB0_123:
	s_add_u32 s8, s60, s12
	s_addc_u32 s33, s61, 0
	s_add_u32 s13, s8, 0x100
	s_addc_u32 s64, s33, 0
	s_and_b64 s[20:21], s[62:63], exec
	s_cselect_b32 s89, s55, s64
	s_cselect_b32 s88, s54, s13
	s_add_u32 s12, s58, s12
	s_addc_u32 s13, s59, 0
	s_add_u32 s20, s12, 0x100
	s_addc_u32 s21, s13, 0
	s_add_i32 s82, 0, 0x10000
	s_and_b64 s[12:13], s[62:63], exec
	s_cselect_b32 vcc_hi, s51, s21
	s_cselect_b32 vcc_lo, s53, s20
	s_add_u32 s12, s8, 0x140080
	s_addc_u32 s13, s33, 0
	s_add_i32 s20, s82, s31
	s_add_i32 m0, s72, 0xc000
	s_add_i32 s34, s72, 0xe000
	s_add_i32 s21, 0, 0x14000
	s_add_i32 s8, s20, 0x2000
	s_add_u32 s66, vcc_lo, 0x10000
	v_add_u32_e32 v140, s82, v180
	s_addc_u32 s67, vcc_hi, 0
	s_add_i32 s33, s21, s31
	ds_read_b128 v[128:131], v140
	ds_read_b128 v[132:135], v140 offset:1024
	ds_read_b128 v[136:139], v140 offset:2048
	ds_read_b128 v[140:143], v140 offset:3072
	s_add_i32 s92, s33, 0x2000
	s_add_i32 s96, 0, 0x18000
	s_add_u32 s64, s88, 0x140000
	s_addc_u32 s65, s89, 0
	s_add_i32 s93, s96, s31
	s_add_i32 s79, 0, 0x1c000
	s_add_i32 s77, s93, 0x2000
	s_add_u32 s62, vcc_lo, 0x10080
	s_addc_u32 s63, vcc_hi, 0
	s_add_i32 s83, s79, s31
	s_add_i32 s82, s83, 0x2000
	v_lshl_add_u64 v[186:187], s[12:13], 0, v[160:161]
	ds_read_b128 v[144:147], v182
	ds_read_b128 v[148:151], v182 offset:1024
	ds_read_b128 v[152:155], v182 offset:2048
	ds_read_b128 v[162:165], v182 offset:3072
	ds_read_b128 v[166:169], v182 offset:4096
	ds_read_b128 v[170:173], v182 offset:5120
	ds_read_b128 v[174:177], v182 offset:6144
	ds_read_b128 v[192:195], v182 offset:7168
	global_load_lds_dwordx4 v[186:187], off
	v_lshl_add_u64 v[186:187], s[12:13], 0, v[158:159]
	s_mov_b32 m0, s34
	s_nop 0
	global_load_lds_dwordx4 v[186:187], off
	s_waitcnt lgkmcnt(8)
	s_barrier
	s_waitcnt lgkmcnt(0)
	s_waitcnt lgkmcnt(0)
	v_mfma_f32_16x16x32_bf16 v[124:127], v[128:131], v[144:147], v[124:127]
	v_mfma_f32_16x16x32_bf16 v[120:123], v[136:139], v[144:147], v[120:123]
	v_mfma_f32_16x16x32_bf16 v[112:115], v[128:131], v[152:155], v[112:115]
	v_mfma_f32_16x16x32_bf16 v[104:107], v[136:139], v[152:155], v[104:107]
	v_mfma_f32_16x16x32_bf16 v[96:99], v[128:131], v[166:169], v[96:99]
	v_mfma_f32_16x16x32_bf16 v[88:91], v[136:139], v[166:169], v[88:91]
	v_mfma_f32_16x16x32_bf16 v[80:83], v[128:131], v[174:177], v[80:83]
	v_mfma_f32_16x16x32_bf16 v[72:75], v[136:139], v[174:177], v[72:75]
	v_mfma_f32_16x16x32_bf16 v[124:127], v[132:135], v[148:151], v[124:127]
	v_mfma_f32_16x16x32_bf16 v[120:123], v[140:143], v[148:151], v[120:123]
	v_mfma_f32_16x16x32_bf16 v[112:115], v[132:135], v[162:165], v[112:115]
	v_mfma_f32_16x16x32_bf16 v[104:107], v[140:143], v[162:165], v[104:107]
	v_mfma_f32_16x16x32_bf16 v[96:99], v[132:135], v[170:173], v[96:99]
	v_mfma_f32_16x16x32_bf16 v[88:91], v[140:143], v[170:173], v[88:91]
	v_mfma_f32_16x16x32_bf16 v[80:83], v[132:135], v[192:195], v[80:83]
	v_mfma_f32_16x16x32_bf16 v[72:75], v[140:143], v[192:195], v[72:75]
	s_barrier
	s_mov_b32 m0, s20
	v_add_u32_e32 v178, s21, v180
	v_lshl_add_u64 v[186:187], vcc, 0, v[184:185]
	ds_read_b128 v[196:199], v178
	ds_read_b128 v[214:217], v178 offset:1024
	ds_read_b128 v[218:221], v178 offset:2048
	ds_read_b128 v[222:225], v178 offset:3072
	global_load_lds_dwordx4 v[186:187], off
	v_lshl_add_u64 v[188:189], vcc, 0, v[156:157]
	s_mov_b32 m0, s8
	s_nop 0
	global_load_lds_dwordx4 v[188:189], off
	s_barrier
	s_waitcnt lgkmcnt(0)
	s_waitcnt lgkmcnt(0)
	v_mfma_f32_16x16x32_bf16 v[116:119], v[196:199], v[144:147], v[116:119]
	v_mfma_f32_16x16x32_bf16 v[108:111], v[218:221], v[144:147], v[108:111]
	v_mfma_f32_16x16x32_bf16 v[100:103], v[196:199], v[152:155], v[100:103]
	v_mfma_f32_16x16x32_bf16 v[92:95], v[218:221], v[152:155], v[92:95]
	v_mfma_f32_16x16x32_bf16 v[84:87], v[196:199], v[166:169], v[84:87]
	v_mfma_f32_16x16x32_bf16 v[76:79], v[218:221], v[166:169], v[76:79]
	v_mfma_f32_16x16x32_bf16 v[68:71], v[196:199], v[174:177], v[68:71]
	v_mfma_f32_16x16x32_bf16 v[64:67], v[218:221], v[174:177], v[64:67]
	v_mfma_f32_16x16x32_bf16 v[116:119], v[214:217], v[148:151], v[116:119]
	v_mfma_f32_16x16x32_bf16 v[108:111], v[222:225], v[148:151], v[108:111]
	v_mfma_f32_16x16x32_bf16 v[100:103], v[214:217], v[162:165], v[100:103]
	v_mfma_f32_16x16x32_bf16 v[92:95], v[222:225], v[162:165], v[92:95]
	v_mfma_f32_16x16x32_bf16 v[84:87], v[214:217], v[170:173], v[84:87]
	v_mfma_f32_16x16x32_bf16 v[76:79], v[222:225], v[170:173], v[76:79]
	v_mfma_f32_16x16x32_bf16 v[68:71], v[214:217], v[192:195], v[68:71]
	v_mfma_f32_16x16x32_bf16 v[64:67], v[222:225], v[192:195], v[64:67]
	s_mov_b32 m0, s72
	v_lshl_add_u64 v[200:201], s[88:89], 0, v[160:161]
	s_barrier
	ds_read_b128 v[144:147], v182 offset:16384
	ds_read_b128 v[148:151], v182 offset:17408
	ds_read_b128 v[152:155], v182 offset:18432
	ds_read_b128 v[162:165], v182 offset:19456
	ds_read_b128 v[166:169], v182 offset:20480
	ds_read_b128 v[170:173], v182 offset:21504
	ds_read_b128 v[174:177], v182 offset:22528
	ds_read_b128 v[192:195], v182 offset:23552
	global_load_lds_dwordx4 v[200:201], off
	v_lshl_add_u64 v[226:227], s[88:89], 0, v[158:159]
	s_mov_b32 m0, s35
	s_nop 0
	global_load_lds_dwordx4 v[226:227], off
	s_barrier
	s_waitcnt lgkmcnt(0)
	s_waitcnt lgkmcnt(0)
	v_mfma_f32_16x16x32_bf16 v[60:63], v[128:131], v[144:147], v[60:63]
	v_mfma_f32_16x16x32_bf16 v[56:59], v[136:139], v[144:147], v[56:59]
	v_mfma_f32_16x16x32_bf16 v[48:51], v[128:131], v[152:155], v[48:51]
	v_mfma_f32_16x16x32_bf16 v[40:43], v[136:139], v[152:155], v[40:43]
	v_mfma_f32_16x16x32_bf16 v[32:35], v[128:131], v[166:169], v[32:35]
	v_mfma_f32_16x16x32_bf16 v[24:27], v[136:139], v[166:169], v[24:27]
	v_mfma_f32_16x16x32_bf16 v[16:19], v[128:131], v[174:177], v[16:19]
	v_mfma_f32_16x16x32_bf16 v[8:11], v[136:139], v[174:177], v[8:11]
	v_mfma_f32_16x16x32_bf16 v[60:63], v[132:135], v[148:151], v[60:63]
	v_mfma_f32_16x16x32_bf16 v[56:59], v[140:143], v[148:151], v[56:59]
	v_mfma_f32_16x16x32_bf16 v[48:51], v[132:135], v[162:165], v[48:51]
	v_mfma_f32_16x16x32_bf16 v[40:43], v[140:143], v[162:165], v[40:43]
	v_mfma_f32_16x16x32_bf16 v[32:35], v[132:135], v[170:173], v[32:35]
	v_mfma_f32_16x16x32_bf16 v[24:27], v[140:143], v[170:173], v[24:27]
	v_mfma_f32_16x16x32_bf16 v[16:19], v[132:135], v[192:195], v[16:19]
	v_mfma_f32_16x16x32_bf16 v[8:11], v[140:143], v[192:195], v[8:11]
	s_barrier
	s_mov_b32 m0, s33
	v_lshl_add_u64 v[128:129], s[66:67], 0, v[184:185]
	global_load_lds_dwordx4 v[128:129], off
	v_lshl_add_u64 v[128:129], s[66:67], 0, v[156:157]
	s_mov_b32 m0, s92
	s_nop 0
	global_load_lds_dwordx4 v[128:129], off
	s_waitcnt vmcnt(6)
	s_barrier
	v_mfma_f32_16x16x32_bf16 v[52:55], v[196:199], v[144:147], v[52:55]
	v_mfma_f32_16x16x32_bf16 v[44:47], v[218:221], v[144:147], v[44:47]
	v_mfma_f32_16x16x32_bf16 v[36:39], v[196:199], v[152:155], v[36:39]
	v_mfma_f32_16x16x32_bf16 v[28:31], v[218:221], v[152:155], v[28:31]
	v_mfma_f32_16x16x32_bf16 v[20:23], v[196:199], v[166:169], v[20:23]
	v_mfma_f32_16x16x32_bf16 v[12:15], v[218:221], v[166:169], v[12:15]
	v_mfma_f32_16x16x32_bf16 v[4:7], v[196:199], v[174:177], v[4:7]
	v_mfma_f32_16x16x32_bf16 v[0:3], v[218:221], v[174:177], v[0:3]
	v_mfma_f32_16x16x32_bf16 v[52:55], v[214:217], v[148:151], v[52:55]
	v_mfma_f32_16x16x32_bf16 v[44:47], v[222:225], v[148:151], v[44:47]
	v_mfma_f32_16x16x32_bf16 v[36:39], v[214:217], v[162:165], v[36:39]
	v_mfma_f32_16x16x32_bf16 v[28:31], v[222:225], v[162:165], v[28:31]
	v_mfma_f32_16x16x32_bf16 v[20:23], v[214:217], v[170:173], v[20:23]
	v_mfma_f32_16x16x32_bf16 v[12:15], v[222:225], v[170:173], v[12:15]
	v_mfma_f32_16x16x32_bf16 v[4:7], v[214:217], v[192:195], v[4:7]
	v_mfma_f32_16x16x32_bf16 v[0:3], v[222:225], v[192:195], v[0:3]
	v_add_u32_e32 v140, s96, v180
	s_barrier
	ds_read_b128 v[128:131], v140
	ds_read_b128 v[132:135], v140 offset:1024
	ds_read_b128 v[136:139], v140 offset:2048
	ds_read_b128 v[140:143], v140 offset:3072
	s_mov_b32 m0, s36
	v_lshl_add_u64 v[196:197], s[64:65], 0, v[160:161]
	ds_read_b128 v[144:147], v182 offset:32768
	ds_read_b128 v[148:151], v182 offset:33792
	ds_read_b128 v[152:155], v182 offset:34816
	ds_read_b128 v[162:165], v182 offset:35840
	ds_read_b128 v[166:169], v182 offset:36864
	ds_read_b128 v[170:173], v182 offset:37888
	ds_read_b128 v[174:177], v182 offset:38912
	ds_read_b128 v[192:195], v182 offset:39936
	global_load_lds_dwordx4 v[196:197], off
	v_lshl_add_u64 v[196:197], s[64:65], 0, v[158:159]
	s_mov_b32 m0, s37
	s_nop 0
	global_load_lds_dwordx4 v[196:197], off
	s_waitcnt lgkmcnt(8)
	s_barrier
	s_waitcnt lgkmcnt(0)
	s_waitcnt lgkmcnt(0)
	v_mfma_f32_16x16x32_bf16 v[124:127], v[128:131], v[144:147], v[124:127]
	v_mfma_f32_16x16x32_bf16 v[120:123], v[136:139], v[144:147], v[120:123]
	v_mfma_f32_16x16x32_bf16 v[112:115], v[128:131], v[152:155], v[112:115]
	v_mfma_f32_16x16x32_bf16 v[104:107], v[136:139], v[152:155], v[104:107]
	v_mfma_f32_16x16x32_bf16 v[96:99], v[128:131], v[166:169], v[96:99]
	v_mfma_f32_16x16x32_bf16 v[88:91], v[136:139], v[166:169], v[88:91]
	v_mfma_f32_16x16x32_bf16 v[80:83], v[128:131], v[174:177], v[80:83]
	v_mfma_f32_16x16x32_bf16 v[72:75], v[136:139], v[174:177], v[72:75]
	v_mfma_f32_16x16x32_bf16 v[124:127], v[132:135], v[148:151], v[124:127]
	v_mfma_f32_16x16x32_bf16 v[120:123], v[140:143], v[148:151], v[120:123]
	v_mfma_f32_16x16x32_bf16 v[112:115], v[132:135], v[162:165], v[112:115]
	v_mfma_f32_16x16x32_bf16 v[104:107], v[140:143], v[162:165], v[104:107]
	v_mfma_f32_16x16x32_bf16 v[96:99], v[132:135], v[170:173], v[96:99]
	v_mfma_f32_16x16x32_bf16 v[88:91], v[140:143], v[170:173], v[88:91]
	v_mfma_f32_16x16x32_bf16 v[80:83], v[132:135], v[192:195], v[80:83]
	v_mfma_f32_16x16x32_bf16 v[72:75], v[140:143], v[192:195], v[72:75]
	s_barrier
	s_mov_b32 m0, s93
	v_add_u32_e32 v178, s79, v180
	v_lshl_add_u64 v[186:187], v[186:187], 0, s[26:27]
	ds_read_b128 v[196:199], v178
	ds_read_b128 v[214:217], v178 offset:1024
	ds_read_b128 v[218:221], v178 offset:2048
	ds_read_b128 v[222:225], v178 offset:3072
	global_load_lds_dwordx4 v[186:187], off
	v_lshl_add_u64 v[186:187], v[188:189], 0, s[26:27]
	s_mov_b32 m0, s77
	s_nop 0
	global_load_lds_dwordx4 v[186:187], off
	s_barrier
	s_waitcnt lgkmcnt(0)
	s_waitcnt lgkmcnt(0)
	v_mfma_f32_16x16x32_bf16 v[116:119], v[196:199], v[144:147], v[116:119]
	v_mfma_f32_16x16x32_bf16 v[108:111], v[218:221], v[144:147], v[108:111]
	v_mfma_f32_16x16x32_bf16 v[100:103], v[196:199], v[152:155], v[100:103]
	v_mfma_f32_16x16x32_bf16 v[92:95], v[218:221], v[152:155], v[92:95]
	v_mfma_f32_16x16x32_bf16 v[84:87], v[196:199], v[166:169], v[84:87]
	v_mfma_f32_16x16x32_bf16 v[76:79], v[218:221], v[166:169], v[76:79]
	v_mfma_f32_16x16x32_bf16 v[68:71], v[196:199], v[174:177], v[68:71]
	v_mfma_f32_16x16x32_bf16 v[64:67], v[218:221], v[174:177], v[64:67]
	v_mfma_f32_16x16x32_bf16 v[116:119], v[214:217], v[148:151], v[116:119]
	v_mfma_f32_16x16x32_bf16 v[108:111], v[222:225], v[148:151], v[108:111]
	v_mfma_f32_16x16x32_bf16 v[100:103], v[214:217], v[162:165], v[100:103]
	v_mfma_f32_16x16x32_bf16 v[92:95], v[222:225], v[162:165], v[92:95]
	v_mfma_f32_16x16x32_bf16 v[84:87], v[214:217], v[170:173], v[84:87]
	v_mfma_f32_16x16x32_bf16 v[76:79], v[222:225], v[170:173], v[76:79]
	v_mfma_f32_16x16x32_bf16 v[68:71], v[214:217], v[192:195], v[68:71]
	v_mfma_f32_16x16x32_bf16 v[64:67], v[222:225], v[192:195], v[64:67]
	s_mov_b32 m0, s39
	v_lshl_add_u64 v[186:187], v[200:201], 0, s[26:27]
	s_barrier
	ds_read_b128 v[144:147], v182 offset:49152
	ds_read_b128 v[148:151], v182 offset:50176
	ds_read_b128 v[152:155], v182 offset:51200
	ds_read_b128 v[162:165], v182 offset:52224
	ds_read_b128 v[166:169], v182 offset:53248
	ds_read_b128 v[170:173], v182 offset:54272
	ds_read_b128 v[174:177], v182 offset:55296
	ds_read_b128 v[192:195], v182 offset:56320
	global_load_lds_dwordx4 v[186:187], off
	v_lshl_add_u64 v[186:187], v[226:227], 0, s[26:27]
	s_mov_b32 m0, s46
	s_nop 0
	global_load_lds_dwordx4 v[186:187], off
	s_barrier
	s_waitcnt lgkmcnt(0)
	s_waitcnt lgkmcnt(0)
	v_mfma_f32_16x16x32_bf16 v[60:63], v[128:131], v[144:147], v[60:63]
	v_mfma_f32_16x16x32_bf16 v[56:59], v[136:139], v[144:147], v[56:59]
	v_mfma_f32_16x16x32_bf16 v[48:51], v[128:131], v[152:155], v[48:51]
	v_mfma_f32_16x16x32_bf16 v[40:43], v[136:139], v[152:155], v[40:43]
	v_mfma_f32_16x16x32_bf16 v[32:35], v[128:131], v[166:169], v[32:35]
	v_mfma_f32_16x16x32_bf16 v[24:27], v[136:139], v[166:169], v[24:27]
	v_mfma_f32_16x16x32_bf16 v[16:19], v[128:131], v[174:177], v[16:19]
	v_mfma_f32_16x16x32_bf16 v[8:11], v[136:139], v[174:177], v[8:11]
	v_mfma_f32_16x16x32_bf16 v[60:63], v[132:135], v[148:151], v[60:63]
	v_mfma_f32_16x16x32_bf16 v[56:59], v[140:143], v[148:151], v[56:59]
	v_mfma_f32_16x16x32_bf16 v[48:51], v[132:135], v[162:165], v[48:51]
	v_mfma_f32_16x16x32_bf16 v[40:43], v[140:143], v[162:165], v[40:43]
	v_mfma_f32_16x16x32_bf16 v[32:35], v[132:135], v[170:173], v[32:35]
	v_mfma_f32_16x16x32_bf16 v[24:27], v[140:143], v[170:173], v[24:27]
	v_mfma_f32_16x16x32_bf16 v[16:19], v[132:135], v[192:195], v[16:19]
	v_mfma_f32_16x16x32_bf16 v[8:11], v[140:143], v[192:195], v[8:11]
	s_barrier
	s_mov_b32 m0, s83
	v_lshl_add_u64 v[128:129], s[62:63], 0, v[184:185]
	global_load_lds_dwordx4 v[128:129], off
	v_lshl_add_u64 v[128:129], s[62:63], 0, v[156:157]
	s_mov_b32 m0, s82
	s_nop 0
	global_load_lds_dwordx4 v[128:129], off
	s_waitcnt vmcnt(6)
	s_barrier
	v_mfma_f32_16x16x32_bf16 v[52:55], v[196:199], v[144:147], v[52:55]
	v_mfma_f32_16x16x32_bf16 v[44:47], v[218:221], v[144:147], v[44:47]
	v_mfma_f32_16x16x32_bf16 v[36:39], v[196:199], v[152:155], v[36:39]
	v_mfma_f32_16x16x32_bf16 v[28:31], v[218:221], v[152:155], v[28:31]
	v_mfma_f32_16x16x32_bf16 v[20:23], v[196:199], v[166:169], v[20:23]
	v_mfma_f32_16x16x32_bf16 v[12:15], v[218:221], v[166:169], v[12:15]
	v_mfma_f32_16x16x32_bf16 v[4:7], v[196:199], v[174:177], v[4:7]
	v_mfma_f32_16x16x32_bf16 v[0:3], v[218:221], v[174:177], v[0:3]
	v_mfma_f32_16x16x32_bf16 v[52:55], v[214:217], v[148:151], v[52:55]
	v_mfma_f32_16x16x32_bf16 v[44:47], v[222:225], v[148:151], v[44:47]
	v_mfma_f32_16x16x32_bf16 v[36:39], v[214:217], v[162:165], v[36:39]
	v_mfma_f32_16x16x32_bf16 v[28:31], v[222:225], v[162:165], v[28:31]
	v_mfma_f32_16x16x32_bf16 v[20:23], v[214:217], v[170:173], v[20:23]
	v_mfma_f32_16x16x32_bf16 v[12:15], v[222:225], v[170:173], v[12:15]
	v_mfma_f32_16x16x32_bf16 v[4:7], v[214:217], v[192:195], v[4:7]
	v_mfma_f32_16x16x32_bf16 v[0:3], v[222:225], v[192:195], v[0:3]
	s_movk_i32 s12, 0x100
	s_andn2_b64 vcc, exec, s[42:43]
	s_mov_b64 s[62:63], -1
	s_mov_b64 s[42:43], 0
	s_barrier
	s_cbranch_vccz .LBB0_123
	s_and_b64 vcc, exec, s[44:45]
	s_cbranch_vccz .LBB0_126
	s_barrier

.LBB0_156:
	s_add_u32 s14, s74, 0x9400000
	s_addc_u32 s15, s75, 0
	s_lshl_b32 s8, s8, 5
	s_and_b32 s8, s8, 0x60
	s_add_i32 m0, s31, 0x18000
	v_lshl_add_u64 v[6:7], v[6:7], 0, s[26:27]
	s_lshl_b32 s37, s13, 6
	s_lshl_b32 s13, s13, 13
	s_lshl_b32 s33, s8, 7
	s_waitcnt vmcnt(2)
	s_barrier
	global_load_lds_dwordx4 v[6:7], off
	v_lshl_add_u64 v[4:5], v[4:5], 0, s[26:27]
	s_add_i32 m0, s31, 0x1a000
	s_add_i32 s38, s31, 0x8000
	s_add_i32 s39, s31, 0xa000
	global_load_lds_dwordx4 v[4:5], off
	v_lshl_add_u64 v[0:1], v[0:1], 0, s[26:27]
	s_mov_b32 m0, s38
	s_add_u32 s20, s56, 0x80080
	global_load_lds_dwordx4 v[0:1], off
	v_lshl_add_u64 v[0:1], v[2:3], 0, s[26:27]
	s_mov_b32 m0, s39
	s_addc_u32 s21, s57, 0
	global_load_lds_dwordx4 v[0:1], off
	s_add_i32 m0, s31, 0x1c000
	v_lshl_add_u64 v[0:1], s[20:21], 0, v[184:185]
	global_load_lds_dwordx4 v[0:1], off
	v_lshl_add_u64 v[0:1], s[20:21], 0, v[128:129]
	s_add_i32 m0, s31, 0x1e000
	v_and_b32_e32 v140, 15, v8
	global_load_lds_dwordx4 v[0:1], off
	v_lshrrev_b32_e32 v0, 1, v8
	v_and_b32_e32 v0, 24, v0
	v_lshlrev_b32_e32 v1, 1, v0
	v_lshlrev_b32_e32 v2, 2, v8
	v_or_b32_e32 v142, s8, v0
	v_lshlrev_b32_e32 v0, 15, v13
	v_lshl_or_b32 v1, v140, 6, v1
	v_and_b32_e32 v2, 32, v2
	v_and_b32_e32 v0, 0xffff0000, v0
	v_bitop3_b32 v3, v1, s13, v2 bitop3:0xde
	v_bitop3_b32 v141, v1, s33, v2 bitop3:0xde
	v_lshl_add_u32 v0, v12, 12, v0
	v_and_b32_e32 v1, 1, v13
	v_lshl_or_b32 v0, v1, 6, v0
	v_lshl_add_u32 v134, v14, 1, v0
	v_lshlrev_b32_e32 v0, 15, v9
	v_and_b32_e32 v0, 0xffff0000, v0
	s_waitcnt vmcnt(6)
	v_lshl_add_u32 v0, v10, 12, v0
	v_and_b32_e32 v1, 1, v9
	s_cmpk_lt_u32 s12, 0x100
	v_lshl_or_b32 v0, v1, 6, v0
	v_readlane_b32 s12, v255, 36
	s_cselect_b64 s[42:43], -1, 0
	v_mov_b32_e32 v135, v185
	v_lshl_add_u32 v136, v11, 1, v0
	v_mov_b32_e32 v137, v185
	s_mov_b32 s50, 0
	v_add_u32_e32 v143, 0, v3
	v_readlane_b32 s51, v255, 23
	s_mov_b32 s58, s12
	s_barrier
	v_readlane_b32 s13, v255, 37
	v_readfirstlane_b32 s98, v203
	s_nop 3
	s_lshr_b32 s98, s98, 8
	s_cmp_lg_u32 s98, 0
	s_cbranch_scc0 .Lgp_159
	s_setprio 1

.LBB0_166:
	s_add_u32 s8, s54, 0xfff80080
	s_addc_u32 s12, s55, -1
	s_add_i32 s20, 0, 0x10000
	s_cmp_eq_u32 s63, 28
	s_cselect_b32 s13, s47, s12
	s_cselect_b32 s12, s59, s8
	v_add_u32_e32 v138, s20, v141
	s_cselect_b32 s57, s45, s62
	s_cselect_b32 s56, s60, s61
	s_add_i32 s8, 0, 0x14000
	ds_read_b128 v[144:147], v138
	ds_read_b128 v[148:151], v138 offset:1024
	ds_read_b128 v[152:155], v138 offset:2048
	ds_read_b128 v[156:159], v138 offset:3072
	v_add_u32_e32 v138, s8, v141
	ds_read_b128 v[160:163], v138
	ds_read_b128 v[164:167], v138 offset:1024
	ds_read_b128 v[168:171], v138 offset:2048
	ds_read_b128 v[172:175], v138 offset:3072
	v_lshl_add_u64 v[138:139], s[54:55], 0, v[134:135]
	s_add_i32 m0, s31, 0xc000
	ds_read_b128 v[176:179], v143
	ds_read_b128 v[180:183], v143 offset:1024
	ds_read_b128 v[192:195], v143 offset:2048
	ds_read_b128 v[196:199], v143 offset:3072
	ds_read_b128 v[214:217], v143 offset:4096
	ds_read_b128 v[218:221], v143 offset:5120
	ds_read_b128 v[222:225], v143 offset:6144
	ds_read_b128 v[226:229], v143 offset:7168
	global_load_lds_dwordx4 v[138:139], off
	v_lshl_add_u64 v[138:139], s[54:55], 0, v[136:137]
	s_add_i32 m0, s31, 0xe000
	s_nop 0
	global_load_lds_dwordx4 v[138:139], off
	s_waitcnt vmcnt(8)
	s_waitcnt lgkmcnt(0)
	s_barrier
	s_waitcnt lgkmcnt(0)
	v_mfma_f32_16x16x32_bf16 v[124:127], v[144:147], v[176:179], v[124:127]
	v_mfma_f32_16x16x32_bf16 v[120:123], v[152:155], v[176:179], v[120:123]
	v_mfma_f32_16x16x32_bf16 v[116:119], v[144:147], v[192:195], v[116:119]
	v_mfma_f32_16x16x32_bf16 v[108:111], v[152:155], v[192:195], v[108:111]
	v_mfma_f32_16x16x32_bf16 v[100:103], v[144:147], v[214:217], v[100:103]
	v_mfma_f32_16x16x32_bf16 v[92:95], v[152:155], v[214:217], v[92:95]
	v_mfma_f32_16x16x32_bf16 v[84:87], v[144:147], v[222:225], v[84:87]
	v_mfma_f32_16x16x32_bf16 v[76:79], v[152:155], v[222:225], v[76:79]
	v_mfma_f32_16x16x32_bf16 v[124:127], v[148:151], v[180:183], v[124:127]
	v_mfma_f32_16x16x32_bf16 v[120:123], v[156:159], v[180:183], v[120:123]
	v_mfma_f32_16x16x32_bf16 v[116:119], v[148:151], v[196:199], v[116:119]
	v_mfma_f32_16x16x32_bf16 v[108:111], v[156:159], v[196:199], v[108:111]
	v_mfma_f32_16x16x32_bf16 v[100:103], v[148:151], v[218:221], v[100:103]
	v_mfma_f32_16x16x32_bf16 v[92:95], v[156:159], v[218:221], v[92:95]
	v_mfma_f32_16x16x32_bf16 v[84:87], v[148:151], v[226:229], v[84:87]
	v_mfma_f32_16x16x32_bf16 v[76:79], v[156:159], v[226:229], v[76:79]
	v_mfma_f32_16x16x32_bf16 v[112:115], v[160:163], v[176:179], v[112:115]
	v_mfma_f32_16x16x32_bf16 v[104:107], v[168:171], v[176:179], v[104:107]
	v_mfma_f32_16x16x32_bf16 v[96:99], v[160:163], v[192:195], v[96:99]
	v_mfma_f32_16x16x32_bf16 v[88:91], v[168:171], v[192:195], v[88:91]
	v_mfma_f32_16x16x32_bf16 v[80:83], v[160:163], v[214:217], v[80:83]
	v_mfma_f32_16x16x32_bf16 v[72:75], v[168:171], v[214:217], v[72:75]
	v_mfma_f32_16x16x32_bf16 v[68:71], v[160:163], v[222:225], v[68:71]
	v_mfma_f32_16x16x32_bf16 v[64:67], v[168:171], v[222:225], v[64:67]
	v_mfma_f32_16x16x32_bf16 v[112:115], v[164:167], v[180:183], v[112:115]
	v_mfma_f32_16x16x32_bf16 v[104:107], v[172:175], v[180:183], v[104:107]
	v_mfma_f32_16x16x32_bf16 v[96:99], v[164:167], v[196:199], v[96:99]
	v_mfma_f32_16x16x32_bf16 v[88:91], v[172:175], v[196:199], v[88:91]
	v_mfma_f32_16x16x32_bf16 v[80:83], v[164:167], v[218:221], v[80:83]
	v_mfma_f32_16x16x32_bf16 v[72:75], v[172:175], v[218:221], v[72:75]
	v_mfma_f32_16x16x32_bf16 v[68:71], v[164:167], v[226:229], v[68:71]
	v_mfma_f32_16x16x32_bf16 v[64:67], v[172:175], v[226:229], v[64:67]
	s_barrier
	s_add_i32 s20, s20, s30
	v_lshl_add_u64 v[138:139], s[56:57], 0, v[184:185]
	s_mov_b32 m0, s20
	ds_read_b128 v[176:179], v143 offset:16384
	ds_read_b128 v[180:183], v143 offset:17408
	ds_read_b128 v[192:195], v143 offset:18432
	ds_read_b128 v[196:199], v143 offset:19456
	ds_read_b128 v[214:217], v143 offset:20480
	ds_read_b128 v[218:221], v143 offset:21504
	ds_read_b128 v[222:225], v143 offset:22528
	ds_read_b128 v[226:229], v143 offset:23552
	global_load_lds_dwordx4 v[138:139], off
	s_add_i32 m0, s20, 0x2000
	s_add_u32 s20, s56, 0x80000
	v_lshl_add_u64 v[186:187], s[56:57], 0, v[128:129]
	s_addc_u32 s21, s57, 0
	s_add_i32 s8, s8, s30
	global_load_lds_dwordx4 v[186:187], off
	v_lshl_add_u64 v[188:189], s[20:21], 0, v[184:185]
	s_mov_b32 m0, s8
	v_lshl_add_u64 v[200:201], s[12:13], 0, v[130:131]
	global_load_lds_dwordx4 v[188:189], off
	v_lshl_add_u64 v[188:189], s[20:21], 0, v[128:129]
	s_add_i32 m0, s8, 0x2000
	s_nop 0
	global_load_lds_dwordx4 v[188:189], off
	v_lshl_add_u64 v[188:189], s[12:13], 0, v[132:133]
	s_mov_b32 m0, s31
	s_nop 0
	global_load_lds_dwordx4 v[188:189], off
	s_mov_b32 m0, s34
	s_nop 0
	global_load_lds_dwordx4 v[200:201], off
	s_waitcnt vmcnt(8)
	s_waitcnt lgkmcnt(0)
	s_barrier
	s_waitcnt lgkmcnt(0)
	v_mfma_f32_16x16x32_bf16 v[60:63], v[144:147], v[176:179], v[60:63]
	v_mfma_f32_16x16x32_bf16 v[56:59], v[152:155], v[176:179], v[56:59]
	v_mfma_f32_16x16x32_bf16 v[52:55], v[144:147], v[192:195], v[52:55]
	v_mfma_f32_16x16x32_bf16 v[44:47], v[152:155], v[192:195], v[44:47]
	v_mfma_f32_16x16x32_bf16 v[36:39], v[144:147], v[214:217], v[36:39]
	v_mfma_f32_16x16x32_bf16 v[28:31], v[152:155], v[214:217], v[28:31]
	v_mfma_f32_16x16x32_bf16 v[20:23], v[144:147], v[222:225], v[20:23]
	v_mfma_f32_16x16x32_bf16 v[12:15], v[152:155], v[222:225], v[12:15]
	v_mfma_f32_16x16x32_bf16 v[60:63], v[148:151], v[180:183], v[60:63]
	v_mfma_f32_16x16x32_bf16 v[56:59], v[156:159], v[180:183], v[56:59]
	v_mfma_f32_16x16x32_bf16 v[52:55], v[148:151], v[196:199], v[52:55]
	v_mfma_f32_16x16x32_bf16 v[44:47], v[156:159], v[196:199], v[44:47]
	v_mfma_f32_16x16x32_bf16 v[36:39], v[148:151], v[218:221], v[36:39]
	v_mfma_f32_16x16x32_bf16 v[28:31], v[156:159], v[218:221], v[28:31]
	v_mfma_f32_16x16x32_bf16 v[20:23], v[148:151], v[226:229], v[20:23]
	v_mfma_f32_16x16x32_bf16 v[12:15], v[156:159], v[226:229], v[12:15]
	v_mfma_f32_16x16x32_bf16 v[48:51], v[160:163], v[176:179], v[48:51]
	v_mfma_f32_16x16x32_bf16 v[40:43], v[168:171], v[176:179], v[40:43]
	v_mfma_f32_16x16x32_bf16 v[32:35], v[160:163], v[192:195], v[32:35]
	v_mfma_f32_16x16x32_bf16 v[24:27], v[168:171], v[192:195], v[24:27]
	v_mfma_f32_16x16x32_bf16 v[16:19], v[160:163], v[214:217], v[16:19]
	v_mfma_f32_16x16x32_bf16 v[8:11], v[168:171], v[214:217], v[8:11]
	v_mfma_f32_16x16x32_bf16 v[4:7], v[160:163], v[222:225], v[4:7]
	v_mfma_f32_16x16x32_bf16 v[0:3], v[168:171], v[222:225], v[0:3]
	v_mfma_f32_16x16x32_bf16 v[48:51], v[164:167], v[180:183], v[48:51]
	v_mfma_f32_16x16x32_bf16 v[40:43], v[172:175], v[180:183], v[40:43]
	v_mfma_f32_16x16x32_bf16 v[32:35], v[164:167], v[196:199], v[32:35]
	v_mfma_f32_16x16x32_bf16 v[24:27], v[172:175], v[196:199], v[24:27]
	v_mfma_f32_16x16x32_bf16 v[16:19], v[164:167], v[218:221], v[16:19]
	v_mfma_f32_16x16x32_bf16 v[8:11], v[172:175], v[218:221], v[8:11]
	v_mfma_f32_16x16x32_bf16 v[4:7], v[164:167], v[226:229], v[4:7]
	v_mfma_f32_16x16x32_bf16 v[0:3], v[172:175], v[226:229], v[0:3]
	s_barrier
	s_add_i32 s8, 0, 0x18000
	s_add_i32 s20, 0, 0x1c000
	v_add_u32_e32 v156, s8, v141
	v_add_u32_e32 v172, s20, v141
	ds_read_b128 v[144:147], v156
	ds_read_b128 v[148:151], v156 offset:1024
	ds_read_b128 v[152:155], v156 offset:2048
	ds_read_b128 v[156:159], v156 offset:3072
	ds_read_b128 v[160:163], v172
	ds_read_b128 v[164:167], v172 offset:1024
	ds_read_b128 v[168:171], v172 offset:2048
	ds_read_b128 v[172:175], v172 offset:3072
	s_add_u32 s12, s12, 0x80000
	s_addc_u32 s13, s13, 0
	s_mov_b32 m0, s35
	v_lshl_add_u64 v[230:231], s[12:13], 0, v[132:133]
	ds_read_b128 v[176:179], v143 offset:32768
	ds_read_b128 v[180:183], v143 offset:33792
	ds_read_b128 v[192:195], v143 offset:34816
	ds_read_b128 v[196:199], v143 offset:35840
	ds_read_b128 v[214:217], v143 offset:36864
	ds_read_b128 v[218:221], v143 offset:37888
	ds_read_b128 v[222:225], v143 offset:38912
	ds_read_b128 v[226:229], v143 offset:39936
	global_load_lds_dwordx4 v[230:231], off
	v_lshl_add_u64 v[230:231], s[12:13], 0, v[130:131]
	s_mov_b32 m0, s36
	s_nop 0
	global_load_lds_dwordx4 v[230:231], off
	s_waitcnt vmcnt(8)
	s_waitcnt lgkmcnt(0)
	s_barrier
	s_waitcnt lgkmcnt(0)
	v_mfma_f32_16x16x32_bf16 v[124:127], v[144:147], v[176:179], v[124:127]
	v_mfma_f32_16x16x32_bf16 v[120:123], v[152:155], v[176:179], v[120:123]
	v_mfma_f32_16x16x32_bf16 v[116:119], v[144:147], v[192:195], v[116:119]
	v_mfma_f32_16x16x32_bf16 v[108:111], v[152:155], v[192:195], v[108:111]
	v_mfma_f32_16x16x32_bf16 v[100:103], v[144:147], v[214:217], v[100:103]
	v_mfma_f32_16x16x32_bf16 v[92:95], v[152:155], v[214:217], v[92:95]
	v_mfma_f32_16x16x32_bf16 v[84:87], v[144:147], v[222:225], v[84:87]
	v_mfma_f32_16x16x32_bf16 v[76:79], v[152:155], v[222:225], v[76:79]
	v_mfma_f32_16x16x32_bf16 v[124:127], v[148:151], v[180:183], v[124:127]
	v_mfma_f32_16x16x32_bf16 v[120:123], v[156:159], v[180:183], v[120:123]
	v_mfma_f32_16x16x32_bf16 v[116:119], v[148:151], v[196:199], v[116:119]
	v_mfma_f32_16x16x32_bf16 v[108:111], v[156:159], v[196:199], v[108:111]
	v_mfma_f32_16x16x32_bf16 v[100:103], v[148:151], v[218:221], v[100:103]
	v_mfma_f32_16x16x32_bf16 v[92:95], v[156:159], v[218:221], v[92:95]
	v_mfma_f32_16x16x32_bf16 v[84:87], v[148:151], v[226:229], v[84:87]
	v_mfma_f32_16x16x32_bf16 v[76:79], v[156:159], v[226:229], v[76:79]
	v_mfma_f32_16x16x32_bf16 v[112:115], v[160:163], v[176:179], v[112:115]
	v_mfma_f32_16x16x32_bf16 v[104:107], v[168:171], v[176:179], v[104:107]
	v_mfma_f32_16x16x32_bf16 v[96:99], v[160:163], v[192:195], v[96:99]
	v_mfma_f32_16x16x32_bf16 v[88:91], v[168:171], v[192:195], v[88:91]
	v_mfma_f32_16x16x32_bf16 v[80:83], v[160:163], v[214:217], v[80:83]
	v_mfma_f32_16x16x32_bf16 v[72:75], v[168:171], v[214:217], v[72:75]
	v_mfma_f32_16x16x32_bf16 v[68:71], v[160:163], v[222:225], v[68:71]
	v_mfma_f32_16x16x32_bf16 v[64:67], v[168:171], v[222:225], v[64:67]
	v_mfma_f32_16x16x32_bf16 v[112:115], v[164:167], v[180:183], v[112:115]
	v_mfma_f32_16x16x32_bf16 v[104:107], v[172:175], v[180:183], v[104:107]
	v_mfma_f32_16x16x32_bf16 v[96:99], v[164:167], v[196:199], v[96:99]
	v_mfma_f32_16x16x32_bf16 v[88:91], v[172:175], v[196:199], v[88:91]
	v_mfma_f32_16x16x32_bf16 v[80:83], v[164:167], v[218:221], v[80:83]
	v_mfma_f32_16x16x32_bf16 v[72:75], v[172:175], v[218:221], v[72:75]
	v_mfma_f32_16x16x32_bf16 v[68:71], v[164:167], v[226:229], v[68:71]
	v_mfma_f32_16x16x32_bf16 v[64:67], v[172:175], v[226:229], v[64:67]
	s_barrier
	s_add_i32 s8, s8, s30
	v_lshl_add_u64 v[138:139], v[138:139], 0, s[26:27]
	s_mov_b32 m0, s8
	ds_read_b128 v[176:179], v143 offset:49152
	ds_read_b128 v[180:183], v143 offset:50176
	ds_read_b128 v[192:195], v143 offset:51200
	ds_read_b128 v[196:199], v143 offset:52224
	ds_read_b128 v[214:217], v143 offset:53248
	ds_read_b128 v[218:221], v143 offset:54272
	ds_read_b128 v[222:225], v143 offset:55296
	ds_read_b128 v[226:229], v143 offset:56320
	global_load_lds_dwordx4 v[138:139], off
	s_add_i32 m0, s8, 0x2000
	s_add_u32 s12, s56, 0x80080
	v_lshl_add_u64 v[138:139], v[186:187], 0, s[26:27]
	s_addc_u32 s13, s57, 0
	s_add_i32 s8, s20, s30
	global_load_lds_dwordx4 v[138:139], off
	v_lshl_add_u64 v[138:139], s[12:13], 0, v[184:185]
	s_mov_b32 m0, s8
	s_nop 0
	global_load_lds_dwordx4 v[138:139], off
	v_lshl_add_u64 v[138:139], s[12:13], 0, v[128:129]
	s_add_i32 m0, s8, 0x2000
	s_nop 0
	global_load_lds_dwordx4 v[138:139], off
	v_lshl_add_u64 v[138:139], v[188:189], 0, s[26:27]
	s_mov_b32 m0, s38
	s_nop 0
	global_load_lds_dwordx4 v[138:139], off
	v_lshl_add_u64 v[138:139], v[200:201], 0, s[26:27]
	s_mov_b32 m0, s39
	s_nop 0
	global_load_lds_dwordx4 v[138:139], off
	s_waitcnt vmcnt(8)
	s_waitcnt lgkmcnt(0)
	s_barrier
	s_waitcnt lgkmcnt(0)
	v_mfma_f32_16x16x32_bf16 v[60:63], v[144:147], v[176:179], v[60:63]
	v_mfma_f32_16x16x32_bf16 v[56:59], v[152:155], v[176:179], v[56:59]
	v_mfma_f32_16x16x32_bf16 v[52:55], v[144:147], v[192:195], v[52:55]
	v_mfma_f32_16x16x32_bf16 v[44:47], v[152:155], v[192:195], v[44:47]
	v_mfma_f32_16x16x32_bf16 v[36:39], v[144:147], v[214:217], v[36:39]
	v_mfma_f32_16x16x32_bf16 v[28:31], v[152:155], v[214:217], v[28:31]
	v_mfma_f32_16x16x32_bf16 v[20:23], v[144:147], v[222:225], v[20:23]
	v_mfma_f32_16x16x32_bf16 v[12:15], v[152:155], v[222:225], v[12:15]
	v_mfma_f32_16x16x32_bf16 v[60:63], v[148:151], v[180:183], v[60:63]
	v_mfma_f32_16x16x32_bf16 v[56:59], v[156:159], v[180:183], v[56:59]
	v_mfma_f32_16x16x32_bf16 v[52:55], v[148:151], v[196:199], v[52:55]
	v_mfma_f32_16x16x32_bf16 v[44:47], v[156:159], v[196:199], v[44:47]
	v_mfma_f32_16x16x32_bf16 v[36:39], v[148:151], v[218:221], v[36:39]
	v_mfma_f32_16x16x32_bf16 v[28:31], v[156:159], v[218:221], v[28:31]
	v_mfma_f32_16x16x32_bf16 v[20:23], v[148:151], v[226:229], v[20:23]
	v_mfma_f32_16x16x32_bf16 v[12:15], v[156:159], v[226:229], v[12:15]
	v_mfma_f32_16x16x32_bf16 v[48:51], v[160:163], v[176:179], v[48:51]
	v_mfma_f32_16x16x32_bf16 v[40:43], v[168:171], v[176:179], v[40:43]
	v_mfma_f32_16x16x32_bf16 v[32:35], v[160:163], v[192:195], v[32:35]
	v_mfma_f32_16x16x32_bf16 v[24:27], v[168:171], v[192:195], v[24:27]
	v_mfma_f32_16x16x32_bf16 v[16:19], v[160:163], v[214:217], v[16:19]
	v_mfma_f32_16x16x32_bf16 v[8:11], v[168:171], v[214:217], v[8:11]
	v_mfma_f32_16x16x32_bf16 v[4:7], v[160:163], v[222:225], v[4:7]
	v_mfma_f32_16x16x32_bf16 v[0:3], v[168:171], v[222:225], v[0:3]
	v_mfma_f32_16x16x32_bf16 v[48:51], v[164:167], v[180:183], v[48:51]
	v_mfma_f32_16x16x32_bf16 v[40:43], v[172:175], v[180:183], v[40:43]
	v_mfma_f32_16x16x32_bf16 v[32:35], v[164:167], v[196:199], v[32:35]
	v_mfma_f32_16x16x32_bf16 v[24:27], v[172:175], v[196:199], v[24:27]
	v_mfma_f32_16x16x32_bf16 v[16:19], v[164:167], v[218:221], v[16:19]
	v_mfma_f32_16x16x32_bf16 v[8:11], v[172:175], v[218:221], v[8:11]
	v_mfma_f32_16x16x32_bf16 v[4:7], v[164:167], v[226:229], v[4:7]
	v_mfma_f32_16x16x32_bf16 v[0:3], v[172:175], v[226:229], v[0:3]
	s_barrier
	s_add_i32 s63, s63, 2
	s_add_u32 s54, s54, 0x100
	s_addc_u32 s55, s55, 0
	s_add_u32 s61, s61, 0x100
	s_addc_u32 s62, s62, 0
	s_cmp_gt_u32 s63, 29
	s_cbranch_scc0 .LBB0_166
	s_and_b64 vcc, exec, s[42:43]
	s_cbranch_vccz .LBB0_169
	s_barrier

.LBB0_523:
	s_setprio 0
	v_readlane_b32 s12, v254, 2
	s_add_i32 s9, s16, 1
	v_readlane_b32 s13, v254, 3
	s_cmp_ge_i32 s9, s13
	s_mov_b64 s[0:1], -1
	v_readlane_b32 s14, v254, 4
	v_readlane_b32 s15, v254, 5
	s_cbranch_scc1 .LBB0_10
	v_readlane_b32 s12, v254, 2
	s_cmp_lg_u32 s16, s12
	v_readlane_b32 s13, v254, 3
	v_readlane_b32 s14, v254, 4
	v_readlane_b32 s15, v254, 5
	s_cbranch_scc0 .LBB0_578
	s_waitcnt vmcnt(0)
	s_waitcnt vmcnt(0) lgkmcnt(0)
	s_barrier
	s_and_saveexec_b64 s[0:1], s[82:83]
	s_cbranch_execz .LBB0_577
	v_readlane_b32 s6, v255, 32
	s_waitcnt vmcnt(0) expcnt(0) lgkmcnt(0)
	s_nop 0
	v_mov_b32_e32 v0, s6
	ds_read_b32 v2, v0
	v_readlane_b32 s6, v255, 33
	s_waitcnt lgkmcnt(0)
	v_cmp_ne_u32_e32 vcc, 0, v2
	v_mov_b32_e32 v0, s6
	ds_read_b32 v0, v0
	s_cbranch_vccnz .LBB0_541
	s_mov_b32 s8, 1
	s_branch .LBB0_529
